# phase-start stagger: blocks 256..511 sleep ~1300 cycles after each grid sync so co-resident blocks run out of phase
# baseline (speedup 1.0000x reference)
; __global__ void __launch_bounds__(256, 2) fwd_megakernel(Params p) {
;     ...
;   for (int ph = p.phase_lo; ph <= p.phase_hi; ++ph) {
;     if (ph > p.phase_lo) grid.sync();
.LBB0_15:
	v_readlane_b32 s48, v236, 0
	s_nop 1
	s_bitcmp1_b32 s48, 8
	s_cbranch_scc0 .Lstag_skip
	s_sleep 20
